# final norm phase pipelined: next row pair loaded before the current pair is reduced and stored
# baseline (speedup 1.0000x reference)
; __device__ __forceinline__ void final_phase(const float* H, const float* g, float* out) {
;     ...
;   for (int row = gw; row < NREAL; row += 2 * nw) {
;     const int row2 = row + nw < NREAL ? row + nw : row;
;     const float* p = H + (size_t)row * DM + lane * 4; const float* p2 = H + (size_t)row2 * DM + lane * 4; f32x4 v[4], u[4]; float ss = 0.f, ss2 = 0.f;
; #pragma unroll
;     for (int i = 0; i < 4; ++i) { v[i] = *(const f32x4*)(p + 256 * i); u[i] = *(const f32x4*)(p2 + 256 * i); }
; #pragma unroll
;     for (int i = 0; i < 4; ++i) { ss += v[i][0] * v[i][0] + v[i][1] * v[i][1] + v[i][2] * v[i][2] + v[i][3] * v[i][3]; ss2 += u[i][0] * u[i][0] + u[i][1] * u[i][1] + u[i][2] * u[i][2] + u[i][3] * u[i][3]; }
;     ss = wave_sum(ss); ss2 = wave_sum(ss2); const float rs = rsqrtf(ss * (1.0f / 1024.0f) + 1e-6f), rs2 = rsqrtf(ss2 * (1.0f / 1024.0f) + 1e-6f);
.LBB0_1577:
	v_readfirstlane_b32 s8, v22
	s_nop 3
	s_lshl_b32 s10, s16, 1
	s_add_i32 s11, s8, s16
	s_cmp_lt_i32 s11, s5
	s_cselect_b32 s11, s11, s8
	s_lshl_b32 s12, s8, 12
	s_lshl_b32 s13, s11, 12
	v_mov_b32_e32 v82, s12
	v_mov_b32_e32 v83, 0
	v_lshl_add_u64 v[84:85], v[16:17], 0, v[82:83]
	v_lshl_add_u64 v[56:57], v[18:19], 0, v[82:83]
	v_mov_b32_e32 v82, s13
	v_lshl_add_u64 v[86:87], v[16:17], 0, v[82:83]
	v_lshl_add_u64 v[60:61], v[18:19], 0, v[82:83]
	global_load_dwordx4 v[24:27], v[84:85], off
	global_load_dwordx4 v[28:31], v[84:85], off offset:1024
	global_load_dwordx4 v[32:35], v[84:85], off offset:2048
	global_load_dwordx4 v[36:39], v[84:85], off offset:3072
	global_load_dwordx4 v[40:43], v[86:87], off
	global_load_dwordx4 v[44:47], v[86:87], off offset:1024
	global_load_dwordx4 v[48:51], v[86:87], off offset:2048
	global_load_dwordx4 v[52:55], v[86:87], off offset:3072
	s_add_i32 s9, s8, s10
	s_cmp_lt_i32 s9, s5
	s_cbranch_scc0 .Lfn_lastA_first
	s_add_i32 s11, s9, s16
	s_cmp_lt_i32 s11, s5
	s_cselect_b32 s11, s11, s9
	s_lshl_b32 s12, s9, 12
	s_lshl_b32 s13, s11, 12
	v_mov_b32_e32 v82, s12
	v_mov_b32_e32 v83, 0
	v_lshl_add_u64 v[84:85], v[16:17], 0, v[82:83]
	v_lshl_add_u64 v[132:133], v[18:19], 0, v[82:83]
	v_mov_b32_e32 v82, s13
	v_lshl_add_u64 v[86:87], v[16:17], 0, v[82:83]
	v_lshl_add_u64 v[134:135], v[18:19], 0, v[82:83]
	global_load_dwordx4 v[100:103], v[84:85], off
	global_load_dwordx4 v[104:107], v[84:85], off offset:1024
	global_load_dwordx4 v[108:111], v[84:85], off offset:2048
	global_load_dwordx4 v[112:115], v[84:85], off offset:3072
	global_load_dwordx4 v[116:119], v[86:87], off
	global_load_dwordx4 v[120:123], v[86:87], off offset:1024
	global_load_dwordx4 v[124:127], v[86:87], off offset:2048
	global_load_dwordx4 v[128:131], v[86:87], off offset:3072
	s_waitcnt vmcnt(8)
	v_lshlrev_b32_e32 v21, 2, v210
	v_xor_b32_e32 v21, 0x80, v21
	v_mov_b32_e32 v23, v21
	v_mov_b32_e32 v62, v25
	v_mov_b32_e32 v63, v29
	v_mov_b32_e32 v70, v33
	v_mov_b32_e32 v71, v37
	v_mov_b32_e32 v58, v24
	v_mov_b32_e32 v59, v28
	v_mov_b32_e32 v68, v32
	v_mov_b32_e32 v69, v36
	v_pk_mul_f32 v[62:63], v[62:63], v[62:63]
	v_pk_mul_f32 v[70:71], v[70:71], v[70:71]
	v_mov_b32_e32 v64, v26
	v_mov_b32_e32 v65, v30
	v_pk_fma_f32 v[58:59], v[58:59], v[58:59], v[62:63]
	v_pk_fma_f32 v[62:63], v[68:69], v[68:69], v[70:71]
	v_mov_b32_e32 v70, v41
	v_mov_b32_e32 v71, v45
	v_mov_b32_e32 v68, v40
	v_mov_b32_e32 v69, v44
	v_mov_b32_e32 v80, v49
	v_mov_b32_e32 v81, v53
	v_pk_fma_f32 v[58:59], v[64:65], v[64:65], v[58:59]
	v_pk_mul_f32 v[64:65], v[70:71], v[70:71]
	v_mov_b32_e32 v66, v27
	v_mov_b32_e32 v67, v31
	v_mov_b32_e32 v76, v42
	v_mov_b32_e32 v77, v46
	v_mov_b32_e32 v78, v48
	v_mov_b32_e32 v79, v52
	v_pk_mul_f32 v[70:71], v[80:81], v[80:81]
	v_pk_fma_f32 v[64:65], v[68:69], v[68:69], v[64:65]
	v_mov_b32_e32 v72, v34
	v_mov_b32_e32 v73, v38
	v_mov_b32_e32 v82, v43
	v_mov_b32_e32 v83, v47
	v_mov_b32_e32 v84, v50
	v_mov_b32_e32 v85, v54
	v_pk_fma_f32 v[58:59], v[66:67], v[66:67], v[58:59]
	v_pk_fma_f32 v[66:67], v[78:79], v[78:79], v[70:71]
	v_pk_fma_f32 v[64:65], v[76:77], v[76:77], v[64:65]
	v_mov_b32_e32 v74, v35
	v_mov_b32_e32 v75, v39
	v_mov_b32_e32 v86, v51
	v_mov_b32_e32 v87, v55
	v_pk_fma_f32 v[62:63], v[72:73], v[72:73], v[62:63]
	v_pk_fma_f32 v[66:67], v[84:85], v[84:85], v[66:67]
	v_pk_fma_f32 v[64:65], v[82:83], v[82:83], v[64:65]
	v_pk_fma_f32 v[62:63], v[74:75], v[74:75], v[62:63]
	v_mov_b32_e32 v69, v58
	v_pk_fma_f32 v[66:67], v[86:87], v[86:87], v[66:67]
	v_mov_b32_e32 v68, v64
	v_mov_b32_e32 v58, v65
	v_mov_b32_e32 v71, v62
	v_mov_b32_e32 v70, v66
	v_pk_add_f32 v[58:59], v[68:69], v[58:59]
	v_mov_b32_e32 v62, v67
	v_pk_add_f32 v[58:59], v[58:59], v[70:71]
	s_nop 0
	v_pk_add_f32 v[58:59], v[58:59], v[62:63]
	ds_swizzle_b32 v63, v59 offset:swizzle(SWAP,16)
	ds_swizzle_b32 v62, v58 offset:swizzle(SWAP,16)
	s_waitcnt lgkmcnt(0)
	v_pk_add_f32 v[58:59], v[58:59], v[62:63]
	ds_swizzle_b32 v63, v59 offset:swizzle(SWAP,8)
	ds_swizzle_b32 v62, v58 offset:swizzle(SWAP,8)
	s_waitcnt lgkmcnt(0)
	v_pk_add_f32 v[58:59], v[58:59], v[62:63]
	ds_swizzle_b32 v63, v59 offset:swizzle(SWAP,4)
	ds_swizzle_b32 v62, v58 offset:swizzle(SWAP,4)
	s_waitcnt lgkmcnt(0)
	v_pk_add_f32 v[58:59], v[58:59], v[62:63]
	ds_swizzle_b32 v63, v59 offset:swizzle(SWAP,2)
	ds_swizzle_b32 v62, v58 offset:swizzle(SWAP,2)
	s_waitcnt lgkmcnt(0)
	v_pk_add_f32 v[58:59], v[58:59], v[62:63]
	ds_swizzle_b32 v63, v59 offset:swizzle(SWAP,1)
	ds_swizzle_b32 v62, v58 offset:swizzle(SWAP,1)
	s_waitcnt lgkmcnt(0)
	v_pk_add_f32 v[58:59], v[58:59], v[62:63]
	ds_bpermute_b32 v63, v21, v59
	ds_bpermute_b32 v62, v23, v58
	s_waitcnt lgkmcnt(0)
; __device__ __forceinline__ void final_phase(const float* H, const float* g, float* out) {
;     ...
;   for (int row = gw; row < NREAL; row += 2 * nw) {
;     const int row2 = row + nw < NREAL ? row + nw : row;
;     const float* p = H + (size_t)row * DM + lane * 4; const float* p2 = H + (size_t)row2 * DM + lane * 4; f32x4 v[4], u[4]; float ss = 0.f, ss2 = 0.f;
; #pragma unroll
;     for (int i = 0; i < 4; ++i) { v[i] = *(const f32x4*)(p + 256 * i); u[i] = *(const f32x4*)(p2 + 256 * i); }
; #pragma unroll
;     for (int i = 0; i < 4; ++i) { ss += v[i][0] * v[i][0] + v[i][1] * v[i][1] + v[i][2] * v[i][2] + v[i][3] * v[i][3]; ss2 += u[i][0] * u[i][0] + u[i][1] * u[i][1] + u[i][2] * u[i][2] + u[i][3] * u[i][3]; }
;     ss = wave_sum(ss); ss2 = wave_sum(ss2); const float rs = rsqrtf(ss * (1.0f / 1024.0f) + 1e-6f), rs2 = rsqrtf(ss2 * (1.0f / 1024.0f) + 1e-6f);
;     float* q = out + (size_t)row * DM + lane * 4; float* q2 = out + (size_t)row2 * DM + lane * 4;
; #pragma unroll
;     for (int i = 0; i < 4; ++i) { *(f32x4*)(q + 256 * i) = v[i] * rs * gv[i]; *(f32x4*)(q2 + 256 * i) = u[i] * rs2 * gv[i]; }
	v_pk_add_f32 v[58:59], v[58:59], v[62:63]
	s_nop 0
	v_pk_fma_f32 v[58:59], v[58:59], s[4:5], v[20:21] op_sel_hi:[1,0,0]
	s_nop 0
	v_mul_f32_e32 v21, 0x4b800000, v59
	v_cmp_gt_f32_e64 s[0:1], s6, v59
	v_mul_f32_e32 v23, 0x4b800000, v58
	v_cmp_gt_f32_e32 vcc, s6, v58
	v_cndmask_b32_e64 v21, v59, v21, s[0:1]
	v_rsq_f32_e32 v21, v21
	v_cndmask_b32_e32 v23, v58, v23, vcc
	v_rsq_f32_e32 v23, v23
	v_mul_f32_e32 v58, 0x45800000, v21
	v_cndmask_b32_e64 v58, v21, v58, s[0:1]
	v_mul_f32_e32 v59, 0x45800000, v23
	v_cndmask_b32_e32 v62, v23, v59, vcc
	v_pk_mul_f32 v[24:25], v[24:25], v[58:59] op_sel_hi:[1,0]
	v_pk_mul_f32 v[26:27], v[26:27], v[58:59] op_sel_hi:[1,0]
	v_pk_mul_f32 v[40:41], v[40:41], v[62:63] op_sel_hi:[1,0]
	v_pk_mul_f32 v[42:43], v[42:43], v[62:63] op_sel_hi:[1,0]
	v_pk_mul_f32 v[64:65], v[28:29], v[58:59] op_sel_hi:[1,0]
	v_pk_mul_f32 v[66:67], v[30:31], v[58:59] op_sel_hi:[1,0]
	v_pk_mul_f32 v[44:45], v[44:45], v[62:63] op_sel_hi:[1,0]
	v_pk_mul_f32 v[46:47], v[46:47], v[62:63] op_sel_hi:[1,0]
	v_pk_mul_f32 v[68:69], v[32:33], v[58:59] op_sel_hi:[1,0]
	v_pk_mul_f32 v[70:71], v[34:35], v[58:59] op_sel_hi:[1,0]
	v_pk_mul_f32 v[48:49], v[48:49], v[62:63] op_sel_hi:[1,0]
	v_pk_mul_f32 v[50:51], v[50:51], v[62:63] op_sel_hi:[1,0]
	v_pk_mul_f32 v[72:73], v[36:37], v[58:59] op_sel_hi:[1,0]
	v_pk_mul_f32 v[58:59], v[38:39], v[58:59] op_sel_hi:[1,0]
	v_pk_mul_f32 v[52:53], v[52:53], v[62:63] op_sel_hi:[1,0]
	v_pk_mul_f32 v[54:55], v[54:55], v[62:63] op_sel_hi:[1,0]
	v_pk_mul_f32 v[26:27], v[2:3], v[26:27]
	v_pk_mul_f32 v[24:25], v[0:1], v[24:25]
	v_pk_mul_f32 v[30:31], v[2:3], v[42:43]
	v_pk_mul_f32 v[28:29], v[0:1], v[40:41]
	v_pk_mul_f32 v[34:35], v[6:7], v[66:67]
	v_pk_mul_f32 v[32:33], v[4:5], v[64:65]
	v_pk_mul_f32 v[38:39], v[6:7], v[46:47]
	v_pk_mul_f32 v[36:37], v[4:5], v[44:45]
	v_pk_mul_f32 v[42:43], v[10:11], v[70:71]
	v_pk_mul_f32 v[40:41], v[8:9], v[68:69]
	v_pk_mul_f32 v[46:47], v[10:11], v[50:51]
	v_pk_mul_f32 v[44:45], v[8:9], v[48:49]
	v_pk_mul_f32 v[50:51], v[14:15], v[58:59]
	v_pk_mul_f32 v[48:49], v[12:13], v[72:73]
	v_pk_mul_f32 v[54:55], v[14:15], v[54:55]
	v_pk_mul_f32 v[52:53], v[12:13], v[52:53]
	global_store_dwordx4 v[56:57], v[24:27], off
	global_store_dwordx4 v[60:61], v[28:31], off
	global_store_dwordx4 v[56:57], v[32:35], off offset:1024
	global_store_dwordx4 v[60:61], v[36:39], off offset:1024
	global_store_dwordx4 v[56:57], v[40:43], off offset:2048
	global_store_dwordx4 v[60:61], v[44:47], off offset:2048
	global_store_dwordx4 v[56:57], v[48:51], off offset:3072
	global_store_dwordx4 v[60:61], v[52:55], off offset:3072
.Lfn_loop:
	s_add_i32 s8, s9, s10
	s_cmp_lt_i32 s8, s5
	s_cbranch_scc0 .Lfn_lastB
	s_add_i32 s11, s8, s16
	s_cmp_lt_i32 s11, s5
	s_cselect_b32 s11, s11, s8
	s_lshl_b32 s12, s8, 12
	s_lshl_b32 s13, s11, 12
	v_mov_b32_e32 v82, s12
	v_mov_b32_e32 v83, 0
	v_lshl_add_u64 v[84:85], v[16:17], 0, v[82:83]
	v_lshl_add_u64 v[56:57], v[18:19], 0, v[82:83]
	v_mov_b32_e32 v82, s13
	v_lshl_add_u64 v[86:87], v[16:17], 0, v[82:83]
	v_lshl_add_u64 v[60:61], v[18:19], 0, v[82:83]
	global_load_dwordx4 v[24:27], v[84:85], off
	global_load_dwordx4 v[28:31], v[84:85], off offset:1024
	global_load_dwordx4 v[32:35], v[84:85], off offset:2048
	global_load_dwordx4 v[36:39], v[84:85], off offset:3072
	global_load_dwordx4 v[40:43], v[86:87], off
	global_load_dwordx4 v[44:47], v[86:87], off offset:1024
	global_load_dwordx4 v[48:51], v[86:87], off offset:2048
	global_load_dwordx4 v[52:55], v[86:87], off offset:3072
	s_waitcnt vmcnt(16)
	v_lshlrev_b32_e32 v21, 2, v210
	v_xor_b32_e32 v21, 0x80, v21
	v_mov_b32_e32 v23, v21
	v_mov_b32_e32 v62, v101
	v_mov_b32_e32 v63, v105
	v_mov_b32_e32 v70, v109
	v_mov_b32_e32 v71, v113
	v_mov_b32_e32 v58, v100
	v_mov_b32_e32 v59, v104
	v_mov_b32_e32 v68, v108
	v_mov_b32_e32 v69, v112
	v_pk_mul_f32 v[62:63], v[62:63], v[62:63]
	v_pk_mul_f32 v[70:71], v[70:71], v[70:71]
	v_mov_b32_e32 v64, v102
	v_mov_b32_e32 v65, v106
	v_pk_fma_f32 v[58:59], v[58:59], v[58:59], v[62:63]
	v_pk_fma_f32 v[62:63], v[68:69], v[68:69], v[70:71]
	v_mov_b32_e32 v70, v117
	v_mov_b32_e32 v71, v121
	v_mov_b32_e32 v68, v116
	v_mov_b32_e32 v69, v120
	v_mov_b32_e32 v80, v125
	v_mov_b32_e32 v81, v129
	v_pk_fma_f32 v[58:59], v[64:65], v[64:65], v[58:59]
	v_pk_mul_f32 v[64:65], v[70:71], v[70:71]
	v_mov_b32_e32 v66, v103
	v_mov_b32_e32 v67, v107
	v_mov_b32_e32 v76, v118
	v_mov_b32_e32 v77, v122
	v_mov_b32_e32 v78, v124
	v_mov_b32_e32 v79, v128
	v_pk_mul_f32 v[70:71], v[80:81], v[80:81]
	v_pk_fma_f32 v[64:65], v[68:69], v[68:69], v[64:65]
	v_mov_b32_e32 v72, v110
	v_mov_b32_e32 v73, v114
	v_mov_b32_e32 v82, v119
	v_mov_b32_e32 v83, v123
	v_mov_b32_e32 v84, v126
	v_mov_b32_e32 v85, v130
	v_pk_fma_f32 v[58:59], v[66:67], v[66:67], v[58:59]
	v_pk_fma_f32 v[66:67], v[78:79], v[78:79], v[70:71]
	v_pk_fma_f32 v[64:65], v[76:77], v[76:77], v[64:65]
	v_mov_b32_e32 v74, v111
	v_mov_b32_e32 v75, v115
	v_mov_b32_e32 v86, v127
	v_mov_b32_e32 v87, v131
	v_pk_fma_f32 v[62:63], v[72:73], v[72:73], v[62:63]
	v_pk_fma_f32 v[66:67], v[84:85], v[84:85], v[66:67]
	v_pk_fma_f32 v[64:65], v[82:83], v[82:83], v[64:65]
	v_pk_fma_f32 v[62:63], v[74:75], v[74:75], v[62:63]
	v_mov_b32_e32 v69, v58
	v_pk_fma_f32 v[66:67], v[86:87], v[86:87], v[66:67]
	v_mov_b32_e32 v68, v64
	v_mov_b32_e32 v58, v65
	v_mov_b32_e32 v71, v62
	v_mov_b32_e32 v70, v66
	v_pk_add_f32 v[58:59], v[68:69], v[58:59]
	v_mov_b32_e32 v62, v67
	v_pk_add_f32 v[58:59], v[58:59], v[70:71]
	s_nop 0
	v_pk_add_f32 v[58:59], v[58:59], v[62:63]
	ds_swizzle_b32 v63, v59 offset:swizzle(SWAP,16)
	ds_swizzle_b32 v62, v58 offset:swizzle(SWAP,16)
	s_waitcnt lgkmcnt(0)
; __device__ __forceinline__ void final_phase(const float* H, const float* g, float* out) {
;     ...
;   for (int row = gw; row < NREAL; row += 2 * nw) {
;     const int row2 = row + nw < NREAL ? row + nw : row;
;     const float* p = H + (size_t)row * DM + lane * 4; const float* p2 = H + (size_t)row2 * DM + lane * 4; f32x4 v[4], u[4]; float ss = 0.f, ss2 = 0.f;
; #pragma unroll
;     for (int i = 0; i < 4; ++i) { v[i] = *(const f32x4*)(p + 256 * i); u[i] = *(const f32x4*)(p2 + 256 * i); }
; #pragma unroll
;     for (int i = 0; i < 4; ++i) { ss += v[i][0] * v[i][0] + v[i][1] * v[i][1] + v[i][2] * v[i][2] + v[i][3] * v[i][3]; ss2 += u[i][0] * u[i][0] + u[i][1] * u[i][1] + u[i][2] * u[i][2] + u[i][3] * u[i][3]; }
;     ss = wave_sum(ss); ss2 = wave_sum(ss2); const float rs = rsqrtf(ss * (1.0f / 1024.0f) + 1e-6f), rs2 = rsqrtf(ss2 * (1.0f / 1024.0f) + 1e-6f);
;     float* q = out + (size_t)row * DM + lane * 4; float* q2 = out + (size_t)row2 * DM + lane * 4;
; #pragma unroll
;     for (int i = 0; i < 4; ++i) { *(f32x4*)(q + 256 * i) = v[i] * rs * gv[i]; *(f32x4*)(q2 + 256 * i) = u[i] * rs2 * gv[i]; }
	v_pk_add_f32 v[58:59], v[58:59], v[62:63]
	ds_swizzle_b32 v63, v59 offset:swizzle(SWAP,8)
	ds_swizzle_b32 v62, v58 offset:swizzle(SWAP,8)
	s_waitcnt lgkmcnt(0)
	v_pk_add_f32 v[58:59], v[58:59], v[62:63]
	ds_swizzle_b32 v63, v59 offset:swizzle(SWAP,4)
	ds_swizzle_b32 v62, v58 offset:swizzle(SWAP,4)
	s_waitcnt lgkmcnt(0)
	v_pk_add_f32 v[58:59], v[58:59], v[62:63]
	ds_swizzle_b32 v63, v59 offset:swizzle(SWAP,2)
	ds_swizzle_b32 v62, v58 offset:swizzle(SWAP,2)
	s_waitcnt lgkmcnt(0)
	v_pk_add_f32 v[58:59], v[58:59], v[62:63]
	ds_swizzle_b32 v63, v59 offset:swizzle(SWAP,1)
	ds_swizzle_b32 v62, v58 offset:swizzle(SWAP,1)
	s_waitcnt lgkmcnt(0)
	v_pk_add_f32 v[58:59], v[58:59], v[62:63]
	ds_bpermute_b32 v63, v21, v59
	ds_bpermute_b32 v62, v23, v58
	s_waitcnt lgkmcnt(0)
	v_pk_add_f32 v[58:59], v[58:59], v[62:63]
	s_nop 0
	v_pk_fma_f32 v[58:59], v[58:59], s[4:5], v[20:21] op_sel_hi:[1,0,0]
	s_nop 0
	v_mul_f32_e32 v21, 0x4b800000, v59
	v_cmp_gt_f32_e64 s[0:1], s6, v59
	v_mul_f32_e32 v23, 0x4b800000, v58
	v_cmp_gt_f32_e32 vcc, s6, v58
	v_cndmask_b32_e64 v21, v59, v21, s[0:1]
	v_rsq_f32_e32 v21, v21
	v_cndmask_b32_e32 v23, v58, v23, vcc
	v_rsq_f32_e32 v23, v23
	v_mul_f32_e32 v58, 0x45800000, v21
	v_cndmask_b32_e64 v58, v21, v58, s[0:1]
	v_mul_f32_e32 v59, 0x45800000, v23
	v_cndmask_b32_e32 v62, v23, v59, vcc
	v_pk_mul_f32 v[100:101], v[100:101], v[58:59] op_sel_hi:[1,0]
	v_pk_mul_f32 v[102:103], v[102:103], v[58:59] op_sel_hi:[1,0]
	v_pk_mul_f32 v[116:117], v[116:117], v[62:63] op_sel_hi:[1,0]
	v_pk_mul_f32 v[118:119], v[118:119], v[62:63] op_sel_hi:[1,0]
	v_pk_mul_f32 v[64:65], v[104:105], v[58:59] op_sel_hi:[1,0]
	v_pk_mul_f32 v[66:67], v[106:107], v[58:59] op_sel_hi:[1,0]
	v_pk_mul_f32 v[120:121], v[120:121], v[62:63] op_sel_hi:[1,0]
	v_pk_mul_f32 v[122:123], v[122:123], v[62:63] op_sel_hi:[1,0]
	v_pk_mul_f32 v[68:69], v[108:109], v[58:59] op_sel_hi:[1,0]
	v_pk_mul_f32 v[70:71], v[110:111], v[58:59] op_sel_hi:[1,0]
	v_pk_mul_f32 v[124:125], v[124:125], v[62:63] op_sel_hi:[1,0]
	v_pk_mul_f32 v[126:127], v[126:127], v[62:63] op_sel_hi:[1,0]
	v_pk_mul_f32 v[72:73], v[112:113], v[58:59] op_sel_hi:[1,0]
	v_pk_mul_f32 v[58:59], v[114:115], v[58:59] op_sel_hi:[1,0]
	v_pk_mul_f32 v[128:129], v[128:129], v[62:63] op_sel_hi:[1,0]
	v_pk_mul_f32 v[130:131], v[130:131], v[62:63] op_sel_hi:[1,0]
	v_pk_mul_f32 v[102:103], v[2:3], v[102:103]
	v_pk_mul_f32 v[100:101], v[0:1], v[100:101]
	v_pk_mul_f32 v[106:107], v[2:3], v[118:119]
	v_pk_mul_f32 v[104:105], v[0:1], v[116:117]
	v_pk_mul_f32 v[110:111], v[6:7], v[66:67]
	v_pk_mul_f32 v[108:109], v[4:5], v[64:65]
	v_pk_mul_f32 v[114:115], v[6:7], v[122:123]
	v_pk_mul_f32 v[112:113], v[4:5], v[120:121]
	v_pk_mul_f32 v[118:119], v[10:11], v[70:71]
	v_pk_mul_f32 v[116:117], v[8:9], v[68:69]
	v_pk_mul_f32 v[122:123], v[10:11], v[126:127]
	v_pk_mul_f32 v[120:121], v[8:9], v[124:125]
	v_pk_mul_f32 v[126:127], v[14:15], v[58:59]
	v_pk_mul_f32 v[124:125], v[12:13], v[72:73]
	v_pk_mul_f32 v[130:131], v[14:15], v[130:131]
	v_pk_mul_f32 v[128:129], v[12:13], v[128:129]
	global_store_dwordx4 v[132:133], v[100:103], off
	global_store_dwordx4 v[134:135], v[104:107], off
	global_store_dwordx4 v[132:133], v[108:111], off offset:1024
	global_store_dwordx4 v[134:135], v[112:115], off offset:1024
	global_store_dwordx4 v[132:133], v[116:119], off offset:2048
	global_store_dwordx4 v[134:135], v[120:123], off offset:2048
	global_store_dwordx4 v[132:133], v[124:127], off offset:3072
	global_store_dwordx4 v[134:135], v[128:131], off offset:3072
	s_add_i32 s9, s8, s10
	s_cmp_lt_i32 s9, s5
	s_cbranch_scc0 .Lfn_lastA
	s_add_i32 s11, s9, s16
	s_cmp_lt_i32 s11, s5
	s_cselect_b32 s11, s11, s9
	s_lshl_b32 s12, s9, 12
	s_lshl_b32 s13, s11, 12
	v_mov_b32_e32 v82, s12
	v_mov_b32_e32 v83, 0
	v_lshl_add_u64 v[84:85], v[16:17], 0, v[82:83]
	v_lshl_add_u64 v[132:133], v[18:19], 0, v[82:83]
	v_mov_b32_e32 v82, s13
	v_lshl_add_u64 v[86:87], v[16:17], 0, v[82:83]
	v_lshl_add_u64 v[134:135], v[18:19], 0, v[82:83]
	global_load_dwordx4 v[100:103], v[84:85], off
	global_load_dwordx4 v[104:107], v[84:85], off offset:1024
	global_load_dwordx4 v[108:111], v[84:85], off offset:2048
	global_load_dwordx4 v[112:115], v[84:85], off offset:3072
	global_load_dwordx4 v[116:119], v[86:87], off
	global_load_dwordx4 v[120:123], v[86:87], off offset:1024
	global_load_dwordx4 v[124:127], v[86:87], off offset:2048
	global_load_dwordx4 v[128:131], v[86:87], off offset:3072
	s_waitcnt vmcnt(16)
	v_lshlrev_b32_e32 v21, 2, v210
	v_xor_b32_e32 v21, 0x80, v21
	v_mov_b32_e32 v23, v21
	v_mov_b32_e32 v62, v25
	v_mov_b32_e32 v63, v29
	v_mov_b32_e32 v70, v33
	v_mov_b32_e32 v71, v37
	v_mov_b32_e32 v58, v24
	v_mov_b32_e32 v59, v28
	v_mov_b32_e32 v68, v32
	v_mov_b32_e32 v69, v36
	v_pk_mul_f32 v[62:63], v[62:63], v[62:63]
	v_pk_mul_f32 v[70:71], v[70:71], v[70:71]
	v_mov_b32_e32 v64, v26
	v_mov_b32_e32 v65, v30
	v_pk_fma_f32 v[58:59], v[58:59], v[58:59], v[62:63]
	v_pk_fma_f32 v[62:63], v[68:69], v[68:69], v[70:71]
	v_mov_b32_e32 v70, v41
	v_mov_b32_e32 v71, v45
	v_mov_b32_e32 v68, v40
	v_mov_b32_e32 v69, v44
	v_mov_b32_e32 v80, v49
	v_mov_b32_e32 v81, v53
	v_pk_fma_f32 v[58:59], v[64:65], v[64:65], v[58:59]
	v_pk_mul_f32 v[64:65], v[70:71], v[70:71]
	v_mov_b32_e32 v66, v27
	v_mov_b32_e32 v67, v31
	v_mov_b32_e32 v76, v42
	v_mov_b32_e32 v77, v46
	v_mov_b32_e32 v78, v48
	v_mov_b32_e32 v79, v52
	v_pk_mul_f32 v[70:71], v[80:81], v[80:81]
	v_pk_fma_f32 v[64:65], v[68:69], v[68:69], v[64:65]
	v_mov_b32_e32 v72, v34
	v_mov_b32_e32 v73, v38
	v_mov_b32_e32 v82, v43
	v_mov_b32_e32 v83, v47
	v_mov_b32_e32 v84, v50
	v_mov_b32_e32 v85, v54
	v_pk_fma_f32 v[58:59], v[66:67], v[66:67], v[58:59]
	v_pk_fma_f32 v[66:67], v[78:79], v[78:79], v[70:71]
	v_pk_fma_f32 v[64:65], v[76:77], v[76:77], v[64:65]
	v_mov_b32_e32 v74, v35
	v_mov_b32_e32 v75, v39
	v_mov_b32_e32 v86, v51
	v_mov_b32_e32 v87, v55
	v_pk_fma_f32 v[62:63], v[72:73], v[72:73], v[62:63]
	v_pk_fma_f32 v[66:67], v[84:85], v[84:85], v[66:67]
	v_pk_fma_f32 v[64:65], v[82:83], v[82:83], v[64:65]
	v_pk_fma_f32 v[62:63], v[74:75], v[74:75], v[62:63]
	v_mov_b32_e32 v69, v58
	v_pk_fma_f32 v[66:67], v[86:87], v[86:87], v[66:67]
	v_mov_b32_e32 v68, v64
	v_mov_b32_e32 v58, v65
	v_mov_b32_e32 v71, v62
	v_mov_b32_e32 v70, v66
	v_pk_add_f32 v[58:59], v[68:69], v[58:59]
	v_mov_b32_e32 v62, v67
	v_pk_add_f32 v[58:59], v[58:59], v[70:71]
	s_nop 0
	v_pk_add_f32 v[58:59], v[58:59], v[62:63]
	ds_swizzle_b32 v63, v59 offset:swizzle(SWAP,16)
	ds_swizzle_b32 v62, v58 offset:swizzle(SWAP,16)
	s_waitcnt lgkmcnt(0)
; __device__ __forceinline__ void final_phase(const float* H, const float* g, float* out) {
;     ...
;   for (int row = gw; row < NREAL; row += 2 * nw) {
;     const int row2 = row + nw < NREAL ? row + nw : row;
;     const float* p = H + (size_t)row * DM + lane * 4; const float* p2 = H + (size_t)row2 * DM + lane * 4; f32x4 v[4], u[4]; float ss = 0.f, ss2 = 0.f;
; #pragma unroll
;     for (int i = 0; i < 4; ++i) { v[i] = *(const f32x4*)(p + 256 * i); u[i] = *(const f32x4*)(p2 + 256 * i); }
; #pragma unroll
;     for (int i = 0; i < 4; ++i) { ss += v[i][0] * v[i][0] + v[i][1] * v[i][1] + v[i][2] * v[i][2] + v[i][3] * v[i][3]; ss2 += u[i][0] * u[i][0] + u[i][1] * u[i][1] + u[i][2] * u[i][2] + u[i][3] * u[i][3]; }
;     ss = wave_sum(ss); ss2 = wave_sum(ss2); const float rs = rsqrtf(ss * (1.0f / 1024.0f) + 1e-6f), rs2 = rsqrtf(ss2 * (1.0f / 1024.0f) + 1e-6f);
;     float* q = out + (size_t)row * DM + lane * 4; float* q2 = out + (size_t)row2 * DM + lane * 4;
; #pragma unroll
;     for (int i = 0; i < 4; ++i) { *(f32x4*)(q + 256 * i) = v[i] * rs * gv[i]; *(f32x4*)(q2 + 256 * i) = u[i] * rs2 * gv[i]; }
	v_pk_add_f32 v[58:59], v[58:59], v[62:63]
	ds_swizzle_b32 v63, v59 offset:swizzle(SWAP,8)
	ds_swizzle_b32 v62, v58 offset:swizzle(SWAP,8)
	s_waitcnt lgkmcnt(0)
	v_pk_add_f32 v[58:59], v[58:59], v[62:63]
	ds_swizzle_b32 v63, v59 offset:swizzle(SWAP,4)
	ds_swizzle_b32 v62, v58 offset:swizzle(SWAP,4)
	s_waitcnt lgkmcnt(0)
	v_pk_add_f32 v[58:59], v[58:59], v[62:63]
	ds_swizzle_b32 v63, v59 offset:swizzle(SWAP,2)
	ds_swizzle_b32 v62, v58 offset:swizzle(SWAP,2)
	s_waitcnt lgkmcnt(0)
	v_pk_add_f32 v[58:59], v[58:59], v[62:63]
	ds_swizzle_b32 v63, v59 offset:swizzle(SWAP,1)
	ds_swizzle_b32 v62, v58 offset:swizzle(SWAP,1)
	s_waitcnt lgkmcnt(0)
	v_pk_add_f32 v[58:59], v[58:59], v[62:63]
	ds_bpermute_b32 v63, v21, v59
	ds_bpermute_b32 v62, v23, v58
	s_waitcnt lgkmcnt(0)
	v_pk_add_f32 v[58:59], v[58:59], v[62:63]
	s_nop 0
	v_pk_fma_f32 v[58:59], v[58:59], s[4:5], v[20:21] op_sel_hi:[1,0,0]
	s_nop 0
	v_mul_f32_e32 v21, 0x4b800000, v59
	v_cmp_gt_f32_e64 s[0:1], s6, v59
	v_mul_f32_e32 v23, 0x4b800000, v58
	v_cmp_gt_f32_e32 vcc, s6, v58
	v_cndmask_b32_e64 v21, v59, v21, s[0:1]
	v_rsq_f32_e32 v21, v21
	v_cndmask_b32_e32 v23, v58, v23, vcc
	v_rsq_f32_e32 v23, v23
	v_mul_f32_e32 v58, 0x45800000, v21
	v_cndmask_b32_e64 v58, v21, v58, s[0:1]
	v_mul_f32_e32 v59, 0x45800000, v23
	v_cndmask_b32_e32 v62, v23, v59, vcc
	v_pk_mul_f32 v[24:25], v[24:25], v[58:59] op_sel_hi:[1,0]
	v_pk_mul_f32 v[26:27], v[26:27], v[58:59] op_sel_hi:[1,0]
	v_pk_mul_f32 v[40:41], v[40:41], v[62:63] op_sel_hi:[1,0]
	v_pk_mul_f32 v[42:43], v[42:43], v[62:63] op_sel_hi:[1,0]
	v_pk_mul_f32 v[64:65], v[28:29], v[58:59] op_sel_hi:[1,0]
	v_pk_mul_f32 v[66:67], v[30:31], v[58:59] op_sel_hi:[1,0]
	v_pk_mul_f32 v[44:45], v[44:45], v[62:63] op_sel_hi:[1,0]
	v_pk_mul_f32 v[46:47], v[46:47], v[62:63] op_sel_hi:[1,0]
	v_pk_mul_f32 v[68:69], v[32:33], v[58:59] op_sel_hi:[1,0]
	v_pk_mul_f32 v[70:71], v[34:35], v[58:59] op_sel_hi:[1,0]
	v_pk_mul_f32 v[48:49], v[48:49], v[62:63] op_sel_hi:[1,0]
	v_pk_mul_f32 v[50:51], v[50:51], v[62:63] op_sel_hi:[1,0]
	v_pk_mul_f32 v[72:73], v[36:37], v[58:59] op_sel_hi:[1,0]
	v_pk_mul_f32 v[58:59], v[38:39], v[58:59] op_sel_hi:[1,0]
	v_pk_mul_f32 v[52:53], v[52:53], v[62:63] op_sel_hi:[1,0]
	v_pk_mul_f32 v[54:55], v[54:55], v[62:63] op_sel_hi:[1,0]
	v_pk_mul_f32 v[26:27], v[2:3], v[26:27]
	v_pk_mul_f32 v[24:25], v[0:1], v[24:25]
	v_pk_mul_f32 v[30:31], v[2:3], v[42:43]
	v_pk_mul_f32 v[28:29], v[0:1], v[40:41]
	v_pk_mul_f32 v[34:35], v[6:7], v[66:67]
	v_pk_mul_f32 v[32:33], v[4:5], v[64:65]
	v_pk_mul_f32 v[38:39], v[6:7], v[46:47]
	v_pk_mul_f32 v[36:37], v[4:5], v[44:45]
	v_pk_mul_f32 v[42:43], v[10:11], v[70:71]
	v_pk_mul_f32 v[40:41], v[8:9], v[68:69]
	v_pk_mul_f32 v[46:47], v[10:11], v[50:51]
	v_pk_mul_f32 v[44:45], v[8:9], v[48:49]
	v_pk_mul_f32 v[50:51], v[14:15], v[58:59]
	v_pk_mul_f32 v[48:49], v[12:13], v[72:73]
	v_pk_mul_f32 v[54:55], v[14:15], v[54:55]
	v_pk_mul_f32 v[52:53], v[12:13], v[52:53]
	global_store_dwordx4 v[56:57], v[24:27], off
	global_store_dwordx4 v[60:61], v[28:31], off
	global_store_dwordx4 v[56:57], v[32:35], off offset:1024
	global_store_dwordx4 v[60:61], v[36:39], off offset:1024
	global_store_dwordx4 v[56:57], v[40:43], off offset:2048
	global_store_dwordx4 v[60:61], v[44:47], off offset:2048
	global_store_dwordx4 v[56:57], v[48:51], off offset:3072
	global_store_dwordx4 v[60:61], v[52:55], off offset:3072
	s_branch .Lfn_loop
.Lfn_lastA_first:
	s_waitcnt vmcnt(0)
	v_lshlrev_b32_e32 v21, 2, v210
	v_xor_b32_e32 v21, 0x80, v21
	v_mov_b32_e32 v23, v21
	v_mov_b32_e32 v62, v25
	v_mov_b32_e32 v63, v29
	v_mov_b32_e32 v70, v33
	v_mov_b32_e32 v71, v37
	v_mov_b32_e32 v58, v24
	v_mov_b32_e32 v59, v28
	v_mov_b32_e32 v68, v32
	v_mov_b32_e32 v69, v36
	v_pk_mul_f32 v[62:63], v[62:63], v[62:63]
	v_pk_mul_f32 v[70:71], v[70:71], v[70:71]
	v_mov_b32_e32 v64, v26
	v_mov_b32_e32 v65, v30
	v_pk_fma_f32 v[58:59], v[58:59], v[58:59], v[62:63]
	v_pk_fma_f32 v[62:63], v[68:69], v[68:69], v[70:71]
	v_mov_b32_e32 v70, v41
	v_mov_b32_e32 v71, v45
	v_mov_b32_e32 v68, v40
	v_mov_b32_e32 v69, v44
	v_mov_b32_e32 v80, v49
	v_mov_b32_e32 v81, v53
	v_pk_fma_f32 v[58:59], v[64:65], v[64:65], v[58:59]
	v_pk_mul_f32 v[64:65], v[70:71], v[70:71]
	v_mov_b32_e32 v66, v27
	v_mov_b32_e32 v67, v31
	v_mov_b32_e32 v76, v42
	v_mov_b32_e32 v77, v46
	v_mov_b32_e32 v78, v48
	v_mov_b32_e32 v79, v52
	v_pk_mul_f32 v[70:71], v[80:81], v[80:81]
	v_pk_fma_f32 v[64:65], v[68:69], v[68:69], v[64:65]
	v_mov_b32_e32 v72, v34
	v_mov_b32_e32 v73, v38
	v_mov_b32_e32 v82, v43
	v_mov_b32_e32 v83, v47
	v_mov_b32_e32 v84, v50
	v_mov_b32_e32 v85, v54
	v_pk_fma_f32 v[58:59], v[66:67], v[66:67], v[58:59]
	v_pk_fma_f32 v[66:67], v[78:79], v[78:79], v[70:71]
	v_pk_fma_f32 v[64:65], v[76:77], v[76:77], v[64:65]
	v_mov_b32_e32 v74, v35
	v_mov_b32_e32 v75, v39
	v_mov_b32_e32 v86, v51
	v_mov_b32_e32 v87, v55
	v_pk_fma_f32 v[62:63], v[72:73], v[72:73], v[62:63]
	v_pk_fma_f32 v[66:67], v[84:85], v[84:85], v[66:67]
	v_pk_fma_f32 v[64:65], v[82:83], v[82:83], v[64:65]
	v_pk_fma_f32 v[62:63], v[74:75], v[74:75], v[62:63]
	v_mov_b32_e32 v69, v58
	v_pk_fma_f32 v[66:67], v[86:87], v[86:87], v[66:67]
	v_mov_b32_e32 v68, v64
	v_mov_b32_e32 v58, v65
	v_mov_b32_e32 v71, v62
	v_mov_b32_e32 v70, v66
	v_pk_add_f32 v[58:59], v[68:69], v[58:59]
	v_mov_b32_e32 v62, v67
	v_pk_add_f32 v[58:59], v[58:59], v[70:71]
	s_nop 0
	v_pk_add_f32 v[58:59], v[58:59], v[62:63]
	ds_swizzle_b32 v63, v59 offset:swizzle(SWAP,16)
	ds_swizzle_b32 v62, v58 offset:swizzle(SWAP,16)
	s_waitcnt lgkmcnt(0)
	v_pk_add_f32 v[58:59], v[58:59], v[62:63]
	ds_swizzle_b32 v63, v59 offset:swizzle(SWAP,8)
	ds_swizzle_b32 v62, v58 offset:swizzle(SWAP,8)
	s_waitcnt lgkmcnt(0)
; __device__ __forceinline__ void final_phase(const float* H, const float* g, float* out) {
;     ...
;   for (int row = gw; row < NREAL; row += 2 * nw) {
;     const int row2 = row + nw < NREAL ? row + nw : row;
;     const float* p = H + (size_t)row * DM + lane * 4; const float* p2 = H + (size_t)row2 * DM + lane * 4; f32x4 v[4], u[4]; float ss = 0.f, ss2 = 0.f;
; #pragma unroll
;     for (int i = 0; i < 4; ++i) { v[i] = *(const f32x4*)(p + 256 * i); u[i] = *(const f32x4*)(p2 + 256 * i); }
; #pragma unroll
;     for (int i = 0; i < 4; ++i) { ss += v[i][0] * v[i][0] + v[i][1] * v[i][1] + v[i][2] * v[i][2] + v[i][3] * v[i][3]; ss2 += u[i][0] * u[i][0] + u[i][1] * u[i][1] + u[i][2] * u[i][2] + u[i][3] * u[i][3]; }
;     ss = wave_sum(ss); ss2 = wave_sum(ss2); const float rs = rsqrtf(ss * (1.0f / 1024.0f) + 1e-6f), rs2 = rsqrtf(ss2 * (1.0f / 1024.0f) + 1e-6f);
;     float* q = out + (size_t)row * DM + lane * 4; float* q2 = out + (size_t)row2 * DM + lane * 4;
; #pragma unroll
;     for (int i = 0; i < 4; ++i) { *(f32x4*)(q + 256 * i) = v[i] * rs * gv[i]; *(f32x4*)(q2 + 256 * i) = u[i] * rs2 * gv[i]; }
	v_pk_add_f32 v[58:59], v[58:59], v[62:63]
	ds_swizzle_b32 v63, v59 offset:swizzle(SWAP,4)
	ds_swizzle_b32 v62, v58 offset:swizzle(SWAP,4)
	s_waitcnt lgkmcnt(0)
	v_pk_add_f32 v[58:59], v[58:59], v[62:63]
	ds_swizzle_b32 v63, v59 offset:swizzle(SWAP,2)
	ds_swizzle_b32 v62, v58 offset:swizzle(SWAP,2)
	s_waitcnt lgkmcnt(0)
	v_pk_add_f32 v[58:59], v[58:59], v[62:63]
	ds_swizzle_b32 v63, v59 offset:swizzle(SWAP,1)
	ds_swizzle_b32 v62, v58 offset:swizzle(SWAP,1)
	s_waitcnt lgkmcnt(0)
	v_pk_add_f32 v[58:59], v[58:59], v[62:63]
	ds_bpermute_b32 v63, v21, v59
	ds_bpermute_b32 v62, v23, v58
	s_waitcnt lgkmcnt(0)
	v_pk_add_f32 v[58:59], v[58:59], v[62:63]
	s_nop 0
	v_pk_fma_f32 v[58:59], v[58:59], s[4:5], v[20:21] op_sel_hi:[1,0,0]
	s_nop 0
	v_mul_f32_e32 v21, 0x4b800000, v59
	v_cmp_gt_f32_e64 s[0:1], s6, v59
	v_mul_f32_e32 v23, 0x4b800000, v58
	v_cmp_gt_f32_e32 vcc, s6, v58
	v_cndmask_b32_e64 v21, v59, v21, s[0:1]
	v_rsq_f32_e32 v21, v21
	v_cndmask_b32_e32 v23, v58, v23, vcc
	v_rsq_f32_e32 v23, v23
	v_mul_f32_e32 v58, 0x45800000, v21
	v_cndmask_b32_e64 v58, v21, v58, s[0:1]
	v_mul_f32_e32 v59, 0x45800000, v23
	v_cndmask_b32_e32 v62, v23, v59, vcc
	v_pk_mul_f32 v[24:25], v[24:25], v[58:59] op_sel_hi:[1,0]
	v_pk_mul_f32 v[26:27], v[26:27], v[58:59] op_sel_hi:[1,0]
	v_pk_mul_f32 v[40:41], v[40:41], v[62:63] op_sel_hi:[1,0]
	v_pk_mul_f32 v[42:43], v[42:43], v[62:63] op_sel_hi:[1,0]
	v_pk_mul_f32 v[64:65], v[28:29], v[58:59] op_sel_hi:[1,0]
	v_pk_mul_f32 v[66:67], v[30:31], v[58:59] op_sel_hi:[1,0]
	v_pk_mul_f32 v[44:45], v[44:45], v[62:63] op_sel_hi:[1,0]
	v_pk_mul_f32 v[46:47], v[46:47], v[62:63] op_sel_hi:[1,0]
	v_pk_mul_f32 v[68:69], v[32:33], v[58:59] op_sel_hi:[1,0]
	v_pk_mul_f32 v[70:71], v[34:35], v[58:59] op_sel_hi:[1,0]
	v_pk_mul_f32 v[48:49], v[48:49], v[62:63] op_sel_hi:[1,0]
	v_pk_mul_f32 v[50:51], v[50:51], v[62:63] op_sel_hi:[1,0]
	v_pk_mul_f32 v[72:73], v[36:37], v[58:59] op_sel_hi:[1,0]
	v_pk_mul_f32 v[58:59], v[38:39], v[58:59] op_sel_hi:[1,0]
	v_pk_mul_f32 v[52:53], v[52:53], v[62:63] op_sel_hi:[1,0]
	v_pk_mul_f32 v[54:55], v[54:55], v[62:63] op_sel_hi:[1,0]
	v_pk_mul_f32 v[26:27], v[2:3], v[26:27]
	v_pk_mul_f32 v[24:25], v[0:1], v[24:25]
	v_pk_mul_f32 v[30:31], v[2:3], v[42:43]
	v_pk_mul_f32 v[28:29], v[0:1], v[40:41]
	v_pk_mul_f32 v[34:35], v[6:7], v[66:67]
	v_pk_mul_f32 v[32:33], v[4:5], v[64:65]
	v_pk_mul_f32 v[38:39], v[6:7], v[46:47]
	v_pk_mul_f32 v[36:37], v[4:5], v[44:45]
	v_pk_mul_f32 v[42:43], v[10:11], v[70:71]
	v_pk_mul_f32 v[40:41], v[8:9], v[68:69]
	v_pk_mul_f32 v[46:47], v[10:11], v[50:51]
	v_pk_mul_f32 v[44:45], v[8:9], v[48:49]
	v_pk_mul_f32 v[50:51], v[14:15], v[58:59]
	v_pk_mul_f32 v[48:49], v[12:13], v[72:73]
	v_pk_mul_f32 v[54:55], v[14:15], v[54:55]
	v_pk_mul_f32 v[52:53], v[12:13], v[52:53]
	global_store_dwordx4 v[56:57], v[24:27], off
	global_store_dwordx4 v[60:61], v[28:31], off
	global_store_dwordx4 v[56:57], v[32:35], off offset:1024
	global_store_dwordx4 v[60:61], v[36:39], off offset:1024
	global_store_dwordx4 v[56:57], v[40:43], off offset:2048
	global_store_dwordx4 v[60:61], v[44:47], off offset:2048
	global_store_dwordx4 v[56:57], v[48:51], off offset:3072
	global_store_dwordx4 v[60:61], v[52:55], off offset:3072
	s_branch .Lfn_done
.Lfn_lastB:
	s_waitcnt vmcnt(0)
	v_lshlrev_b32_e32 v21, 2, v210
	v_xor_b32_e32 v21, 0x80, v21
	v_mov_b32_e32 v23, v21
	v_mov_b32_e32 v62, v101
	v_mov_b32_e32 v63, v105
	v_mov_b32_e32 v70, v109
	v_mov_b32_e32 v71, v113
	v_mov_b32_e32 v58, v100
	v_mov_b32_e32 v59, v104
	v_mov_b32_e32 v68, v108
	v_mov_b32_e32 v69, v112
	v_pk_mul_f32 v[62:63], v[62:63], v[62:63]
	v_pk_mul_f32 v[70:71], v[70:71], v[70:71]
	v_mov_b32_e32 v64, v102
	v_mov_b32_e32 v65, v106
	v_pk_fma_f32 v[58:59], v[58:59], v[58:59], v[62:63]
	v_pk_fma_f32 v[62:63], v[68:69], v[68:69], v[70:71]
	v_mov_b32_e32 v70, v117
	v_mov_b32_e32 v71, v121
	v_mov_b32_e32 v68, v116
	v_mov_b32_e32 v69, v120
	v_mov_b32_e32 v80, v125
	v_mov_b32_e32 v81, v129
	v_pk_fma_f32 v[58:59], v[64:65], v[64:65], v[58:59]
	v_pk_mul_f32 v[64:65], v[70:71], v[70:71]
	v_mov_b32_e32 v66, v103
	v_mov_b32_e32 v67, v107
	v_mov_b32_e32 v76, v118
	v_mov_b32_e32 v77, v122
	v_mov_b32_e32 v78, v124
	v_mov_b32_e32 v79, v128
	v_pk_mul_f32 v[70:71], v[80:81], v[80:81]
	v_pk_fma_f32 v[64:65], v[68:69], v[68:69], v[64:65]
	v_mov_b32_e32 v72, v110
	v_mov_b32_e32 v73, v114
	v_mov_b32_e32 v82, v119
	v_mov_b32_e32 v83, v123
	v_mov_b32_e32 v84, v126
	v_mov_b32_e32 v85, v130
	v_pk_fma_f32 v[58:59], v[66:67], v[66:67], v[58:59]
	v_pk_fma_f32 v[66:67], v[78:79], v[78:79], v[70:71]
	v_pk_fma_f32 v[64:65], v[76:77], v[76:77], v[64:65]
	v_mov_b32_e32 v74, v111
	v_mov_b32_e32 v75, v115
	v_mov_b32_e32 v86, v127
	v_mov_b32_e32 v87, v131
	v_pk_fma_f32 v[62:63], v[72:73], v[72:73], v[62:63]
	v_pk_fma_f32 v[66:67], v[84:85], v[84:85], v[66:67]
	v_pk_fma_f32 v[64:65], v[82:83], v[82:83], v[64:65]
	v_pk_fma_f32 v[62:63], v[74:75], v[74:75], v[62:63]
	v_mov_b32_e32 v69, v58
	v_pk_fma_f32 v[66:67], v[86:87], v[86:87], v[66:67]
	v_mov_b32_e32 v68, v64
	v_mov_b32_e32 v58, v65
	v_mov_b32_e32 v71, v62
	v_mov_b32_e32 v70, v66
	v_pk_add_f32 v[58:59], v[68:69], v[58:59]
	v_mov_b32_e32 v62, v67
	v_pk_add_f32 v[58:59], v[58:59], v[70:71]
	s_nop 0
	v_pk_add_f32 v[58:59], v[58:59], v[62:63]
	ds_swizzle_b32 v63, v59 offset:swizzle(SWAP,16)
	ds_swizzle_b32 v62, v58 offset:swizzle(SWAP,16)
	s_waitcnt lgkmcnt(0)
	v_pk_add_f32 v[58:59], v[58:59], v[62:63]
	ds_swizzle_b32 v63, v59 offset:swizzle(SWAP,8)
	ds_swizzle_b32 v62, v58 offset:swizzle(SWAP,8)
	s_waitcnt lgkmcnt(0)
	v_pk_add_f32 v[58:59], v[58:59], v[62:63]
	ds_swizzle_b32 v63, v59 offset:swizzle(SWAP,4)
	ds_swizzle_b32 v62, v58 offset:swizzle(SWAP,4)
	s_waitcnt lgkmcnt(0)
; __device__ __forceinline__ void final_phase(const float* H, const float* g, float* out) {
;     ...
;     ss = wave_sum(ss); ss2 = wave_sum(ss2); const float rs = rsqrtf(ss * (1.0f / 1024.0f) + 1e-6f), rs2 = rsqrtf(ss2 * (1.0f / 1024.0f) + 1e-6f);
;     float* q = out + (size_t)row * DM + lane * 4; float* q2 = out + (size_t)row2 * DM + lane * 4;
; #pragma unroll
;     for (int i = 0; i < 4; ++i) { *(f32x4*)(q + 256 * i) = v[i] * rs * gv[i]; *(f32x4*)(q2 + 256 * i) = u[i] * rs2 * gv[i]; }
	v_pk_add_f32 v[58:59], v[58:59], v[62:63]
	ds_swizzle_b32 v63, v59 offset:swizzle(SWAP,2)
	ds_swizzle_b32 v62, v58 offset:swizzle(SWAP,2)
	s_waitcnt lgkmcnt(0)
	v_pk_add_f32 v[58:59], v[58:59], v[62:63]
	ds_swizzle_b32 v63, v59 offset:swizzle(SWAP,1)
	ds_swizzle_b32 v62, v58 offset:swizzle(SWAP,1)
	s_waitcnt lgkmcnt(0)
	v_pk_add_f32 v[58:59], v[58:59], v[62:63]
	ds_bpermute_b32 v63, v21, v59
	ds_bpermute_b32 v62, v23, v58
	s_waitcnt lgkmcnt(0)
	v_pk_add_f32 v[58:59], v[58:59], v[62:63]
	s_nop 0
	v_pk_fma_f32 v[58:59], v[58:59], s[4:5], v[20:21] op_sel_hi:[1,0,0]
	s_nop 0
	v_mul_f32_e32 v21, 0x4b800000, v59
	v_cmp_gt_f32_e64 s[0:1], s6, v59
	v_mul_f32_e32 v23, 0x4b800000, v58
	v_cmp_gt_f32_e32 vcc, s6, v58
	v_cndmask_b32_e64 v21, v59, v21, s[0:1]
	v_rsq_f32_e32 v21, v21
	v_cndmask_b32_e32 v23, v58, v23, vcc
	v_rsq_f32_e32 v23, v23
	v_mul_f32_e32 v58, 0x45800000, v21
	v_cndmask_b32_e64 v58, v21, v58, s[0:1]
	v_mul_f32_e32 v59, 0x45800000, v23
	v_cndmask_b32_e32 v62, v23, v59, vcc
	v_pk_mul_f32 v[100:101], v[100:101], v[58:59] op_sel_hi:[1,0]
	v_pk_mul_f32 v[102:103], v[102:103], v[58:59] op_sel_hi:[1,0]
	v_pk_mul_f32 v[116:117], v[116:117], v[62:63] op_sel_hi:[1,0]
	v_pk_mul_f32 v[118:119], v[118:119], v[62:63] op_sel_hi:[1,0]
	v_pk_mul_f32 v[64:65], v[104:105], v[58:59] op_sel_hi:[1,0]
	v_pk_mul_f32 v[66:67], v[106:107], v[58:59] op_sel_hi:[1,0]
	v_pk_mul_f32 v[120:121], v[120:121], v[62:63] op_sel_hi:[1,0]
	v_pk_mul_f32 v[122:123], v[122:123], v[62:63] op_sel_hi:[1,0]
	v_pk_mul_f32 v[68:69], v[108:109], v[58:59] op_sel_hi:[1,0]
	v_pk_mul_f32 v[70:71], v[110:111], v[58:59] op_sel_hi:[1,0]
	v_pk_mul_f32 v[124:125], v[124:125], v[62:63] op_sel_hi:[1,0]
	v_pk_mul_f32 v[126:127], v[126:127], v[62:63] op_sel_hi:[1,0]
	v_pk_mul_f32 v[72:73], v[112:113], v[58:59] op_sel_hi:[1,0]
	v_pk_mul_f32 v[58:59], v[114:115], v[58:59] op_sel_hi:[1,0]
	v_pk_mul_f32 v[128:129], v[128:129], v[62:63] op_sel_hi:[1,0]
	v_pk_mul_f32 v[130:131], v[130:131], v[62:63] op_sel_hi:[1,0]
	v_pk_mul_f32 v[102:103], v[2:3], v[102:103]
	v_pk_mul_f32 v[100:101], v[0:1], v[100:101]
	v_pk_mul_f32 v[106:107], v[2:3], v[118:119]
	v_pk_mul_f32 v[104:105], v[0:1], v[116:117]
	v_pk_mul_f32 v[110:111], v[6:7], v[66:67]
	v_pk_mul_f32 v[108:109], v[4:5], v[64:65]
	v_pk_mul_f32 v[114:115], v[6:7], v[122:123]
	v_pk_mul_f32 v[112:113], v[4:5], v[120:121]
	v_pk_mul_f32 v[118:119], v[10:11], v[70:71]
	v_pk_mul_f32 v[116:117], v[8:9], v[68:69]
	v_pk_mul_f32 v[122:123], v[10:11], v[126:127]
	v_pk_mul_f32 v[120:121], v[8:9], v[124:125]
	v_pk_mul_f32 v[126:127], v[14:15], v[58:59]
	v_pk_mul_f32 v[124:125], v[12:13], v[72:73]
	v_pk_mul_f32 v[130:131], v[14:15], v[130:131]
	v_pk_mul_f32 v[128:129], v[12:13], v[128:129]
	global_store_dwordx4 v[132:133], v[100:103], off
	global_store_dwordx4 v[134:135], v[104:107], off
	global_store_dwordx4 v[132:133], v[108:111], off offset:1024
	global_store_dwordx4 v[134:135], v[112:115], off offset:1024
	global_store_dwordx4 v[132:133], v[116:119], off offset:2048
	global_store_dwordx4 v[134:135], v[120:123], off offset:2048
	global_store_dwordx4 v[132:133], v[124:127], off offset:3072
	global_store_dwordx4 v[134:135], v[128:131], off offset:3072
	s_branch .Lfn_done
; __device__ __forceinline__ void final_phase(const float* H, const float* g, float* out) {
;     ...
;   for (int row = gw; row < NREAL; row += 2 * nw) {
;     const int row2 = row + nw < NREAL ? row + nw : row;
;     const float* p = H + (size_t)row * DM + lane * 4; const float* p2 = H + (size_t)row2 * DM + lane * 4; f32x4 v[4], u[4]; float ss = 0.f, ss2 = 0.f;
; #pragma unroll
;     for (int i = 0; i < 4; ++i) { v[i] = *(const f32x4*)(p + 256 * i); u[i] = *(const f32x4*)(p2 + 256 * i); }
; #pragma unroll
;     for (int i = 0; i < 4; ++i) { ss += v[i][0] * v[i][0] + v[i][1] * v[i][1] + v[i][2] * v[i][2] + v[i][3] * v[i][3]; ss2 += u[i][0] * u[i][0] + u[i][1] * u[i][1] + u[i][2] * u[i][2] + u[i][3] * u[i][3]; }
;     ss = wave_sum(ss); ss2 = wave_sum(ss2); const float rs = rsqrtf(ss * (1.0f / 1024.0f) + 1e-6f), rs2 = rsqrtf(ss2 * (1.0f / 1024.0f) + 1e-6f);
;     float* q = out + (size_t)row * DM + lane * 4; float* q2 = out + (size_t)row2 * DM + lane * 4;
; #pragma unroll
;     for (int i = 0; i < 4; ++i) { *(f32x4*)(q + 256 * i) = v[i] * rs * gv[i]; *(f32x4*)(q2 + 256 * i) = u[i] * rs2 * gv[i]; }
.Lfn_lastA:
	s_waitcnt vmcnt(0)
	v_lshlrev_b32_e32 v21, 2, v210
	v_xor_b32_e32 v21, 0x80, v21
	v_mov_b32_e32 v23, v21
	v_mov_b32_e32 v62, v25
	v_mov_b32_e32 v63, v29
	v_mov_b32_e32 v70, v33
	v_mov_b32_e32 v71, v37
	v_mov_b32_e32 v58, v24
	v_mov_b32_e32 v59, v28
	v_mov_b32_e32 v68, v32
	v_mov_b32_e32 v69, v36
	v_pk_mul_f32 v[62:63], v[62:63], v[62:63]
	v_pk_mul_f32 v[70:71], v[70:71], v[70:71]
	v_mov_b32_e32 v64, v26
	v_mov_b32_e32 v65, v30
	v_pk_fma_f32 v[58:59], v[58:59], v[58:59], v[62:63]
	v_pk_fma_f32 v[62:63], v[68:69], v[68:69], v[70:71]
	v_mov_b32_e32 v70, v41
	v_mov_b32_e32 v71, v45
	v_mov_b32_e32 v68, v40
	v_mov_b32_e32 v69, v44
	v_mov_b32_e32 v80, v49
	v_mov_b32_e32 v81, v53
	v_pk_fma_f32 v[58:59], v[64:65], v[64:65], v[58:59]
	v_pk_mul_f32 v[64:65], v[70:71], v[70:71]
	v_mov_b32_e32 v66, v27
	v_mov_b32_e32 v67, v31
	v_mov_b32_e32 v76, v42
	v_mov_b32_e32 v77, v46
	v_mov_b32_e32 v78, v48
	v_mov_b32_e32 v79, v52
	v_pk_mul_f32 v[70:71], v[80:81], v[80:81]
	v_pk_fma_f32 v[64:65], v[68:69], v[68:69], v[64:65]
	v_mov_b32_e32 v72, v34
	v_mov_b32_e32 v73, v38
	v_mov_b32_e32 v82, v43
	v_mov_b32_e32 v83, v47
	v_mov_b32_e32 v84, v50
	v_mov_b32_e32 v85, v54
	v_pk_fma_f32 v[58:59], v[66:67], v[66:67], v[58:59]
	v_pk_fma_f32 v[66:67], v[78:79], v[78:79], v[70:71]
	v_pk_fma_f32 v[64:65], v[76:77], v[76:77], v[64:65]
	v_mov_b32_e32 v74, v35
	v_mov_b32_e32 v75, v39
	v_mov_b32_e32 v86, v51
	v_mov_b32_e32 v87, v55
	v_pk_fma_f32 v[62:63], v[72:73], v[72:73], v[62:63]
	v_pk_fma_f32 v[66:67], v[84:85], v[84:85], v[66:67]
	v_pk_fma_f32 v[64:65], v[82:83], v[82:83], v[64:65]
	v_pk_fma_f32 v[62:63], v[74:75], v[74:75], v[62:63]
	v_mov_b32_e32 v69, v58
	v_pk_fma_f32 v[66:67], v[86:87], v[86:87], v[66:67]
	v_mov_b32_e32 v68, v64
	v_mov_b32_e32 v58, v65
	v_mov_b32_e32 v71, v62
	v_mov_b32_e32 v70, v66
	v_pk_add_f32 v[58:59], v[68:69], v[58:59]
	v_mov_b32_e32 v62, v67
	v_pk_add_f32 v[58:59], v[58:59], v[70:71]
	s_nop 0
	v_pk_add_f32 v[58:59], v[58:59], v[62:63]
	ds_swizzle_b32 v63, v59 offset:swizzle(SWAP,16)
	ds_swizzle_b32 v62, v58 offset:swizzle(SWAP,16)
	s_waitcnt lgkmcnt(0)
	v_pk_add_f32 v[58:59], v[58:59], v[62:63]
	ds_swizzle_b32 v63, v59 offset:swizzle(SWAP,8)
	ds_swizzle_b32 v62, v58 offset:swizzle(SWAP,8)
	s_waitcnt lgkmcnt(0)
	v_pk_add_f32 v[58:59], v[58:59], v[62:63]
	ds_swizzle_b32 v63, v59 offset:swizzle(SWAP,4)
	ds_swizzle_b32 v62, v58 offset:swizzle(SWAP,4)
	s_waitcnt lgkmcnt(0)
	v_pk_add_f32 v[58:59], v[58:59], v[62:63]
	ds_swizzle_b32 v63, v59 offset:swizzle(SWAP,2)
	ds_swizzle_b32 v62, v58 offset:swizzle(SWAP,2)
	s_waitcnt lgkmcnt(0)
	v_pk_add_f32 v[58:59], v[58:59], v[62:63]
	ds_swizzle_b32 v63, v59 offset:swizzle(SWAP,1)
	ds_swizzle_b32 v62, v58 offset:swizzle(SWAP,1)
	s_waitcnt lgkmcnt(0)
	v_pk_add_f32 v[58:59], v[58:59], v[62:63]
	ds_bpermute_b32 v63, v21, v59
	ds_bpermute_b32 v62, v23, v58
	s_waitcnt lgkmcnt(0)
	v_pk_add_f32 v[58:59], v[58:59], v[62:63]
	s_nop 0
	v_pk_fma_f32 v[58:59], v[58:59], s[4:5], v[20:21] op_sel_hi:[1,0,0]
	s_nop 0
	v_mul_f32_e32 v21, 0x4b800000, v59
	v_cmp_gt_f32_e64 s[0:1], s6, v59
	v_mul_f32_e32 v23, 0x4b800000, v58
	v_cmp_gt_f32_e32 vcc, s6, v58
	v_cndmask_b32_e64 v21, v59, v21, s[0:1]
	v_rsq_f32_e32 v21, v21
	v_cndmask_b32_e32 v23, v58, v23, vcc
	v_rsq_f32_e32 v23, v23
	v_mul_f32_e32 v58, 0x45800000, v21
	v_cndmask_b32_e64 v58, v21, v58, s[0:1]
	v_mul_f32_e32 v59, 0x45800000, v23
	v_cndmask_b32_e32 v62, v23, v59, vcc
	v_pk_mul_f32 v[24:25], v[24:25], v[58:59] op_sel_hi:[1,0]
	v_pk_mul_f32 v[26:27], v[26:27], v[58:59] op_sel_hi:[1,0]
	v_pk_mul_f32 v[40:41], v[40:41], v[62:63] op_sel_hi:[1,0]
	v_pk_mul_f32 v[42:43], v[42:43], v[62:63] op_sel_hi:[1,0]
	v_pk_mul_f32 v[64:65], v[28:29], v[58:59] op_sel_hi:[1,0]
	v_pk_mul_f32 v[66:67], v[30:31], v[58:59] op_sel_hi:[1,0]
	v_pk_mul_f32 v[44:45], v[44:45], v[62:63] op_sel_hi:[1,0]
	v_pk_mul_f32 v[46:47], v[46:47], v[62:63] op_sel_hi:[1,0]
	v_pk_mul_f32 v[68:69], v[32:33], v[58:59] op_sel_hi:[1,0]
	v_pk_mul_f32 v[70:71], v[34:35], v[58:59] op_sel_hi:[1,0]
	v_pk_mul_f32 v[48:49], v[48:49], v[62:63] op_sel_hi:[1,0]
	v_pk_mul_f32 v[50:51], v[50:51], v[62:63] op_sel_hi:[1,0]
	v_pk_mul_f32 v[72:73], v[36:37], v[58:59] op_sel_hi:[1,0]
	v_pk_mul_f32 v[58:59], v[38:39], v[58:59] op_sel_hi:[1,0]
	v_pk_mul_f32 v[52:53], v[52:53], v[62:63] op_sel_hi:[1,0]
	v_pk_mul_f32 v[54:55], v[54:55], v[62:63] op_sel_hi:[1,0]
	v_pk_mul_f32 v[26:27], v[2:3], v[26:27]
	v_pk_mul_f32 v[24:25], v[0:1], v[24:25]
	v_pk_mul_f32 v[30:31], v[2:3], v[42:43]
	v_pk_mul_f32 v[28:29], v[0:1], v[40:41]
	v_pk_mul_f32 v[34:35], v[6:7], v[66:67]
	v_pk_mul_f32 v[32:33], v[4:5], v[64:65]
	v_pk_mul_f32 v[38:39], v[6:7], v[46:47]
	v_pk_mul_f32 v[36:37], v[4:5], v[44:45]
	v_pk_mul_f32 v[42:43], v[10:11], v[70:71]
	v_pk_mul_f32 v[40:41], v[8:9], v[68:69]
	v_pk_mul_f32 v[46:47], v[10:11], v[50:51]
	v_pk_mul_f32 v[44:45], v[8:9], v[48:49]
	v_pk_mul_f32 v[50:51], v[14:15], v[58:59]
	v_pk_mul_f32 v[48:49], v[12:13], v[72:73]
	v_pk_mul_f32 v[54:55], v[14:15], v[54:55]
	v_pk_mul_f32 v[52:53], v[12:13], v[52:53]
	global_store_dwordx4 v[56:57], v[24:27], off
	global_store_dwordx4 v[60:61], v[28:31], off
	global_store_dwordx4 v[56:57], v[32:35], off offset:1024
	global_store_dwordx4 v[60:61], v[36:39], off offset:1024
	global_store_dwordx4 v[56:57], v[40:43], off offset:2048
	global_store_dwordx4 v[60:61], v[44:47], off offset:2048
	global_store_dwordx4 v[56:57], v[48:51], off offset:3072
	global_store_dwordx4 v[60:61], v[52:55], off offset:3072
.Lfn_done:
.LBB0_1578:
	s_endpgm
